# stack2 plus: B latent half-tiles execute the 17 accumulator/row-sum carry copies only on the skipped-tile path
# baseline (speedup 1.0000x reference)
; template <int MODE, int NKB> ...
;     ...
;     for (int i = 0; i < NKB; ++i) { const LAS bf16_t* kp = Ks + (kb0 + 16 * i + l15) * KST + 8 * quad;
; #pragma unroll
;         for (int s = 0; s < NS; ++s) st[s][i] = (f32x4){negm, negm, negm, negm};
; #pragma unroll
;         for (int kc = 0; kc < 2; ++kc) {
;             if (MODE == 2) {
; #pragma unroll
;                 for (int s = 0; s < NS; ++s) { const bf16x8 a = *(const LAS bf16x8*)(kp + 64 * s + 32 * kc); st[s][i] = __builtin_amdgcn_mfma_f32_16x16x32_bf16(a, qf[s][kc], st[s][i], 0, 0, 0); }
;                 if (kc == 1 && (i & 1)) __builtin_amdgcn_sched_barrier(0);
;             } else { const bf16x8 a = *(const LAS bf16x8*)(kp + 32 * kc);
; #pragma unroll
;                 for (int s = 0; s < NS; ++s) st[s][i] = __builtin_amdgcn_mfma_f32_16x16x32_bf16(a, qf[s][kc], st[s][i], 0, 0, 0); } } }
;     if (MODE == 2) __builtin_amdgcn_sched_barrier(0);
;     if (masked) {
;         if (MODE == 0) {
; #pragma unroll
;             for (int i = 0; i < NKB; ++i)
; #pragma unroll
;                 for (int r = 0; r < 4; ++r) { const int d = mp - (kb0 + 16 * i + 4 * quad + r); const bool bad = (d > 128) || (d < -128);
; #pragma unroll
;                     for (int s = 0; s < NS; ++s) st[s][i][r] = bad ? NEGBIG : st[s][i][r]; }
;         }
;         if (MODE == 1) {
; #pragma unroll
;             for (int i = 0; i < NKB; ++i)
; #pragma unroll
;                 for (int r = 0; r < 4; ++r) { const int key = kb0 + 16 * i + 4 * quad + r; const bool valid = (key >= mp) && (key < mp + 16);
;                     const float bias = valid ? brow[key] : 0.f; st[0][i][r] = valid ? st[0][i][r] + bias : NEGBIG; }
;         }
;     }
;     bf16x8 pf[NS][NKB / 2];
; #pragma unroll
;     for (int s = 0; s < NS; ++s) {
;         if (MODE == 2) __builtin_amdgcn_sched_barrier(0);
;         float ps = 0.f;
; #pragma unroll
;         for (int i = 0; i < NKB; ++i)
; #pragma unroll
;             for (int r = 0; r < 4; ++r) { const float p = fast_exp2(st[s][i][r]); st[s][i][r] = p; ps += p; }
;         lsum[s] += ps;
; #pragma unroll
;         for (int c = 0; c < NKB / 2; ++c) { u32x4 pw; pw.x = pk2(st[s][2 * c][0], st[s][2 * c][1]); pw.y = pk2(st[s][2 * c][2], st[s][2 * c][3]); pw.z = pk2(st[s][2 * c + 1][0], st[s][2 * c + 1][1]); pw.w = pk2(st[s][2 * c + 1][2], st[s][2 * c + 1][3]);
;             pf[s][c] = __builtin_bit_cast(bf16x8, pw); }
.LBB0_463:
	s_bitcmp1_b32 s70, 0
	s_cselect_b32 s26, 0x9000, 0
	s_add_i32 s69, s26, 0
	s_cmp_gt_u32 s70, 1
	s_cselect_b64 s[26:27], -1, 0
	s_mov_b64 s[28:29], -1
	s_and_b64 vcc, exec, s[26:27]
	s_cbranch_vccz .LBB0_483
	s_cmp_ge_i32 s61, s36
	s_cselect_b64 s[28:29], -1, 0
	s_min_i32 s70, s60, s65
	s_cmp_gt_i32 s70, s61
	s_cselect_b64 s[70:71], -1, 0
	s_and_b64 s[28:29], s[70:71], s[28:29]
	s_andn2_b64 vcc, exec, s[28:29]
	s_cbranch_vccnz .Lbocopy_h0
	v_add3_u32 v92, s69, v133, v110
	ds_read_b128 v[84:87], v92
	ds_read_b128 v[88:91], v92 offset:64
	s_waitcnt lgkmcnt(1)
	v_mfma_f32_16x16x32_bf16 v[84:87], v[84:87], v[28:31], v[24:27]
	s_waitcnt lgkmcnt(0)
	v_mfma_f32_16x16x32_bf16 v[88:91], v[88:91], v[32:35], v[84:87]
	s_nop 5
	ds_read_b128 v[84:87], v92 offset:2304
	ds_read_b128 v[92:95], v92 offset:2368
	s_waitcnt lgkmcnt(1)
	v_mfma_f32_16x16x32_bf16 v[84:87], v[84:87], v[28:31], v[24:27]
	s_waitcnt lgkmcnt(0)
	v_mfma_f32_16x16x32_bf16 v[84:87], v[92:95], v[32:35], v[84:87]
	v_add_u32_e32 v124, s68, v118
	v_add_u32_e32 v124, 0x121b0, v124
	ds_read2_b32 v[96:97], v124 offset1:1
	ds_read2_b32 v[98:99], v124 offset0:2 offset1:3
	ds_read2_b32 v[126:127], v124 offset0:16 offset1:17
	ds_read2_b32 v[128:129], v124 offset0:18 offset1:19
	s_waitcnt lgkmcnt(0)
	v_add_f32_e32 v96, v88, v96
	v_add_f32_e32 v97, v89, v97
	v_add_f32_e32 v98, v90, v98
	v_add_f32_e32 v99, v91, v99
	v_add_f32_e32 v126, v84, v126
	v_add_f32_e32 v127, v85, v127
	v_add_f32_e32 v128, v86, v128
	v_add_f32_e32 v129, v87, v129
	v_cndmask_b32_e64 v93, v231, v96, s[6:7]
	v_cndmask_b32_e64 v92, v231, v97, s[14:15]
	v_cndmask_b32_e64 v89, v231, v98, s[16:17]
	v_cndmask_b32_e64 v88, v231, v99, s[18:19]
	v_cndmask_b32_e64 v91, v231, v126, s[20:21]
	v_cndmask_b32_e64 v90, v231, v127, s[22:23]
	v_cndmask_b32_e64 v85, v231, v128, s[24:25]
	v_cndmask_b32_e64 v84, v231, v129, s[4:5]
	v_exp_f32_e32 v86, v93
	v_exp_f32_e32 v92, v92
	v_exp_f32_e32 v89, v89
	v_exp_f32_e32 v88, v88
	v_add_f32_e32 v87, 0, v86
	v_exp_f32_e32 v91, v91
	v_add_f32_e32 v87, v87, v92
	v_exp_f32_e32 v90, v90
	v_add_f32_e32 v87, v87, v89
	v_exp_f32_e32 v85, v85
	v_add_f32_e32 v87, v87, v88
	v_exp_f32_e32 v84, v84
	v_add_f32_e32 v87, v87, v91
	s_lshl_b32 s28, s47, 1
	v_add_f32_e32 v87, v87, v90
	s_add_i32 s28, s69, s28
	v_add_f32_e32 v87, v87, v85
	v_add3_u32 v124, s28, v120, v111
	v_add_f32_e32 v87, v87, v84
	v_cvt_pk_bf16_f32 v96, v86, v92
	v_cvt_pk_bf16_f32 v97, v89, v88
	v_cvt_pk_bf16_f32 v99, v85, v84
	v_add_u32_e32 v84, 0x4800, v124
	v_add_u32_e32 v88, 0x5800, v124
	v_add_u32_e32 v92, 0x6800, v124
	v_add_u32_e32 v124, 0x7800, v124
	v_add_f32_e32 v125, v119, v87
	v_cvt_pk_bf16_f32 v98, v91, v90
	ds_read2_b64 v[84:87], v84 offset1:4
	ds_read2_b64 v[88:91], v88 offset0:32 offset1:36
	ds_read2_b64 v[92:95], v92 offset0:64 offset1:68
	ds_read2_b64 v[126:129], v124 offset0:96 offset1:100
	s_waitcnt lgkmcnt(3)
	v_mfma_f32_16x16x32_bf16 v[84:87], v[84:87], v[96:99], v[68:71]
	s_waitcnt lgkmcnt(2)
	v_mfma_f32_16x16x32_bf16 v[88:91], v[88:91], v[96:99], v[72:75]
	s_waitcnt lgkmcnt(1)
	v_mfma_f32_16x16x32_bf16 v[92:95], v[92:95], v[96:99], v[76:79]
	s_waitcnt lgkmcnt(0)
	v_mfma_f32_16x16x32_bf16 v[96:99], v[126:129], v[96:99], v[80:83]
	s_branch .LBB0_482
.Lbocopy_h0:
	v_mov_b32_e32 v99, v83
	v_mov_b32_e32 v98, v82
	v_mov_b32_e32 v97, v81
	v_mov_b32_e32 v96, v80
	v_mov_b32_e32 v95, v79
	v_mov_b32_e32 v94, v78
	v_mov_b32_e32 v93, v77
	v_mov_b32_e32 v92, v76
	v_mov_b32_e32 v91, v75
	v_mov_b32_e32 v90, v74
	v_mov_b32_e32 v89, v73
	v_mov_b32_e32 v88, v72
	v_mov_b32_e32 v87, v71
	v_mov_b32_e32 v86, v70
	v_mov_b32_e32 v85, v69
	v_mov_b32_e32 v84, v68
	v_mov_b32_e32 v125, v119

; template <int MODE, int NKB> ...
;     ...
;     for (int i = 0; i < NKB; ++i) { const LAS bf16_t* kp = Ks + (kb0 + 16 * i + l15) * KST + 8 * quad;
; #pragma unroll
;         for (int s = 0; s < NS; ++s) st[s][i] = (f32x4){negm, negm, negm, negm};
; #pragma unroll
;         for (int kc = 0; kc < 2; ++kc) {
;             if (MODE == 2) {
; #pragma unroll
;                 for (int s = 0; s < NS; ++s) { const bf16x8 a = *(const LAS bf16x8*)(kp + 64 * s + 32 * kc); st[s][i] = __builtin_amdgcn_mfma_f32_16x16x32_bf16(a, qf[s][kc], st[s][i], 0, 0, 0); }
;                 if (kc == 1 && (i & 1)) __builtin_amdgcn_sched_barrier(0);
;             } else { const bf16x8 a = *(const LAS bf16x8*)(kp + 32 * kc);
; #pragma unroll
;                 for (int s = 0; s < NS; ++s) st[s][i] = __builtin_amdgcn_mfma_f32_16x16x32_bf16(a, qf[s][kc], st[s][i], 0, 0, 0); } } }
;     if (MODE == 2) __builtin_amdgcn_sched_barrier(0);
;     if (masked) {
;         if (MODE == 0) {
; #pragma unroll
;             for (int i = 0; i < NKB; ++i)
; #pragma unroll
;                 for (int r = 0; r < 4; ++r) { const int d = mp - (kb0 + 16 * i + 4 * quad + r); const bool bad = (d > 128) || (d < -128);
; #pragma unroll
;                     for (int s = 0; s < NS; ++s) st[s][i][r] = bad ? NEGBIG : st[s][i][r]; }
;         }
;         if (MODE == 1) {
; #pragma unroll
;             for (int i = 0; i < NKB; ++i)
; #pragma unroll
;                 for (int r = 0; r < 4; ++r) { const int key = kb0 + 16 * i + 4 * quad + r; const bool valid = (key >= mp) && (key < mp + 16);
;                     const float bias = valid ? brow[key] : 0.f; st[0][i][r] = valid ? st[0][i][r] + bias : NEGBIG; }
;         }
;     }
;     bf16x8 pf[NS][NKB / 2];
; #pragma unroll
;     for (int s = 0; s < NS; ++s) {
;         if (MODE == 2) __builtin_amdgcn_sched_barrier(0);
;         float ps = 0.f;
; #pragma unroll
;         for (int i = 0; i < NKB; ++i)
; #pragma unroll
;             for (int r = 0; r < 4; ++r) { const float p = fast_exp2(st[s][i][r]); st[s][i][r] = p; ps += p; }
;         lsum[s] += ps;
; #pragma unroll
;         for (int c = 0; c < NKB / 2; ++c) { u32x4 pw; pw.x = pk2(st[s][2 * c][0], st[s][2 * c][1]); pw.y = pk2(st[s][2 * c][2], st[s][2 * c][3]); pw.z = pk2(st[s][2 * c + 1][0], st[s][2 * c + 1][1]); pw.w = pk2(st[s][2 * c + 1][2], st[s][2 * c + 1][3]);
;             pf[s][c] = __builtin_bit_cast(bf16x8, pw); }
.LBB0_485:
	s_andn2_b64 vcc, exec, s[26:27]
	s_mov_b64 s[26:27], -1
	s_cbranch_vccnz .LBB0_505
	s_add_i32 s28, s61, 1
	s_cmp_ge_i32 s28, s36
	s_cselect_b64 s[26:27], -1, 0
	s_min_i32 s29, s60, s65
	s_cmp_gt_i32 s29, s28
	s_cselect_b64 s[28:29], -1, 0
	s_and_b64 s[26:27], s[28:29], s[26:27]
	s_andn2_b64 vcc, exec, s[26:27]
	s_cbranch_vccnz .Lbocopy_h1
	v_add3_u32 v76, s69, v133, v110
	ds_read_b128 v[68:71], v76 offset:9216
	ds_read_b128 v[72:75], v76 offset:9280
	s_waitcnt lgkmcnt(1)
	v_mfma_f32_16x16x32_bf16 v[68:71], v[68:71], v[28:31], v[24:27]
	s_waitcnt lgkmcnt(0)
	v_mfma_f32_16x16x32_bf16 v[72:75], v[72:75], v[32:35], v[68:71]
	s_nop 5
	ds_read_b128 v[68:71], v76 offset:11520
	ds_read_b128 v[76:79], v76 offset:11584
	s_waitcnt lgkmcnt(1)
	v_mfma_f32_16x16x32_bf16 v[68:71], v[68:71], v[28:31], v[24:27]
	s_waitcnt lgkmcnt(0)
	v_mfma_f32_16x16x32_bf16 v[68:71], v[76:79], v[32:35], v[68:71]
	v_add_u32_e32 v78, s68, v118
	v_add_u32_e32 v78, 0x1222c, v78
	ds_read2_b32 v[80:81], v78 offset1:1
	ds_read2_b32 v[82:83], v78 offset0:2 offset1:3
	ds_read2_b32 v[128:129], v78 offset0:16 offset1:17
	ds_read2_b32 v[130:131], v78 offset0:18 offset1:19
	s_waitcnt lgkmcnt(0)
	v_add_f32_e32 v80, v72, v80
	v_add_f32_e32 v81, v73, v81
	v_add_f32_e32 v82, v74, v82
	v_add_f32_e32 v83, v75, v83
	v_add_f32_e32 v128, v68, v128
	v_add_f32_e32 v129, v69, v129
	v_add_f32_e32 v130, v70, v130
	v_add_f32_e32 v131, v71, v131
	v_cndmask_b32_e64 v77, v231, v80, s[6:7]
	v_cndmask_b32_e64 v76, v231, v81, s[14:15]
	v_cndmask_b32_e64 v73, v231, v82, s[16:17]
	v_cndmask_b32_e64 v72, v231, v83, s[18:19]
	v_cndmask_b32_e64 v75, v231, v128, s[20:21]
	v_cndmask_b32_e64 v74, v231, v129, s[22:23]
	v_cndmask_b32_e64 v69, v231, v130, s[24:25]
	v_cndmask_b32_e64 v68, v231, v131, s[4:5]
	v_exp_f32_e32 v70, v77
	v_exp_f32_e32 v76, v76
	v_exp_f32_e32 v73, v73
	v_exp_f32_e32 v72, v72
	v_add_f32_e32 v71, 0, v70
	v_exp_f32_e32 v75, v75
	v_add_f32_e32 v71, v71, v76
	v_exp_f32_e32 v74, v74
	v_add_f32_e32 v71, v71, v73
	v_exp_f32_e32 v69, v69
	v_add_f32_e32 v71, v71, v72
	v_exp_f32_e32 v68, v68
	v_add_f32_e32 v71, v71, v75
	s_lshl_b32 s26, s47, 1
	v_add_f32_e32 v71, v71, v74
	s_add_i32 s69, s69, s26
	v_add_f32_e32 v71, v71, v69
	v_add3_u32 v127, s69, v120, v111
	v_add_f32_e32 v71, v71, v68
	v_cvt_pk_bf16_f32 v80, v70, v76
	v_cvt_pk_bf16_f32 v81, v73, v72
	v_cvt_pk_bf16_f32 v83, v69, v68
	v_add_u32_e32 v68, 0x4800, v127
	v_add_u32_e32 v72, 0x5800, v127
	v_add_u32_e32 v76, 0x6800, v127
	v_add_u32_e32 v127, 0x7800, v127
	v_add_f32_e32 v119, v125, v71
	v_cvt_pk_bf16_f32 v82, v75, v74
	ds_read2_b64 v[68:71], v68 offset0:16 offset1:20
	ds_read2_b64 v[72:75], v72 offset0:48 offset1:52
	ds_read2_b64 v[76:79], v76 offset0:80 offset1:84
	ds_read2_b64 v[128:131], v127 offset0:112 offset1:116
	s_waitcnt lgkmcnt(3)
	v_mfma_f32_16x16x32_bf16 v[68:71], v[68:71], v[80:83], v[84:87]
	s_waitcnt lgkmcnt(2)
	v_mfma_f32_16x16x32_bf16 v[72:75], v[72:75], v[80:83], v[88:91]
	s_waitcnt lgkmcnt(1)
	v_mfma_f32_16x16x32_bf16 v[76:79], v[76:79], v[80:83], v[92:95]
	s_waitcnt lgkmcnt(0)
	v_mfma_f32_16x16x32_bf16 v[80:83], v[128:131], v[80:83], v[96:99]
	s_branch .LBB0_504
.Lbocopy_h1:
	v_mov_b32_e32 v83, v99
	v_mov_b32_e32 v82, v98
	v_mov_b32_e32 v81, v97
	v_mov_b32_e32 v80, v96
	v_mov_b32_e32 v79, v95
	v_mov_b32_e32 v78, v94
	v_mov_b32_e32 v77, v93
	v_mov_b32_e32 v76, v92
	v_mov_b32_e32 v75, v91
	v_mov_b32_e32 v74, v90
	v_mov_b32_e32 v73, v89
	v_mov_b32_e32 v72, v88
	v_mov_b32_e32 v71, v87
	v_mov_b32_e32 v70, v86
	v_mov_b32_e32 v69, v85
	v_mov_b32_e32 v68, v84
	v_mov_b32_e32 v119, v125
